# GEMM K-loop pointer-select head made branch-free (unreachable second-K-segment arm removed) in P1,P4,P5,P6,P7
# speedup vs baseline: 1.0043x; 1.0043x over previous
.LBB0_163:
	s_cmpk_eq_i32 s56, 0x700
	s_cselect_b64 s[62:63], -1, 0
	s_add_u32 s64, s42, s56
	s_addc_u32 s65, s43, s57
	s_add_u32 s94, s38, s56
	s_addc_u32 s93, s39, s57
	s_add_u32 s58, s64, 0x180
	s_addc_u32 s59, s65, 0
	s_add_u32 s60, s94, 0x180
	s_addc_u32 s61, s93, 0
	s_cmpk_eq_i32 s56, 0x700
	s_cselect_b32 s58, s48, s58
	s_cselect_b32 s59, s49, s59
	s_cselect_b32 s60, s54, s60
	s_cselect_b32 s61, s55, s61
	s_branch .LBB0_162

.LBB0_715:
	s_cmpk_eq_i32 s48, 0x700
	s_cselect_b64 s[54:55], -1, 0
	s_add_u32 s56, s44, s48
	s_addc_u32 s57, s45, s49
	s_add_u32 s84, s38, s48
	s_addc_u32 s83, s39, s49
	s_add_u32 s50, s56, 0x180
	s_addc_u32 s51, s57, 0
	s_add_u32 s52, s84, 0x180
	s_addc_u32 s53, s83, 0
	s_cmpk_eq_i32 s48, 0x700
	s_cselect_b32 s50, s36, s50
	s_cselect_b32 s51, s37, s51
	s_cselect_b32 s52, s46, s52
	s_cselect_b32 s53, s47, s53
	s_branch .LBB0_714

.LBB0_807:
	s_cmpk_eq_i32 s44, 0x700
	s_cselect_b64 s[50:51], -1, 0
	s_add_u32 s52, s30, s44
	s_addc_u32 s53, s31, s45
	s_add_u32 s83, s28, s44
	s_addc_u32 s82, s29, s45
	s_add_u32 s46, s52, 0x180
	s_addc_u32 s47, s53, 0
	s_add_u32 s48, s83, 0x180
	s_addc_u32 s49, s82, 0
	s_cmpk_eq_i32 s44, 0x700
	s_cselect_b32 s46, s36, s46
	s_cselect_b32 s47, s37, s47
	s_cselect_b32 s48, s38, s48
	s_cselect_b32 s49, s39, s49
	s_branch .LBB0_806

.LBB0_897:
	s_cmpk_eq_i32 s36, 0x1500
	s_cselect_b64 s[44:45], -1, 0
	s_add_u32 s46, s26, s36
	s_addc_u32 s47, s27, s37
	s_add_u32 s80, s24, s36
	s_addc_u32 s79, s25, s37
	s_add_u32 s38, s46, 0x180
	s_addc_u32 s39, s47, 0
	s_add_u32 s40, s80, 0x180
	s_addc_u32 s41, s79, 0
	s_cmpk_eq_i32 s36, 0x1500
	s_cselect_b32 s38, s28, s38
	s_cselect_b32 s39, s29, s39
	s_cselect_b32 s40, s30, s40
	s_cselect_b32 s41, s31, s41
	s_branch .LBB0_896

.LBB0_1019:
	s_cmpk_eq_i32 s38, 0x700
	s_cselect_b64 s[44:45], -1, 0
	s_add_u32 s46, s28, s38
	s_addc_u32 s47, s29, s39
	s_add_u32 s73, s26, s38
	s_addc_u32 s72, s27, s39
	s_add_u32 s40, s46, 0x180
	s_addc_u32 s41, s47, 0
	s_add_u32 s42, s73, 0x180
	s_addc_u32 s43, s72, 0
	s_cmpk_eq_i32 s38, 0x700
	s_cselect_b32 s40, s30, s40
	s_cselect_b32 s41, s31, s41
	s_cselect_b32 s42, s36, s42
	s_cselect_b32 s43, s37, s43
	s_branch .LBB0_1018
